# speedup vs baseline: 1.0453x; 1.0211x over previous
; #define STAGE_A(Poff, off, hrow) do { const unsigned _s = (off) + (unsigned)(hrow) * lda2;                                \
;     GLDS(ldsw + (Poff), offA, srdA, _s); GLDS(ldsw + (Poff) + 8192, offA, srdA, _s + lda128); } while (0)
; #define STAGE_B(Poff, off, hrow) do { const unsigned _s = (off) + (unsigned)(hrow) * ldb2;                                \
;     GLDS(ldsw + (Poff), offB, srdB, _s); GLDS(ldsw + (Poff) + 8192, offB, srdB, _s + ldb128); } while (0)
; #define LDA(dst, b, h) _Pragma("unroll") for (int m = 0; m < 4; ++m) _Pragma("unroll") for (int k = 0; k < 2; ++k) \
;     dst[m][k] = *reinterpret_cast<const bf16x8*>((const char*)SA(b, h) + aoff + (m * 2 + k) * 1024)
; #define LDB(dst, b, h) _Pragma("unroll") for (int n = 0; n < 2; ++n) _Pragma("unroll") for (int k = 0; k < 2; ++k) \
;     dst[n][k] = *reinterpret_cast<const bf16x8*>((const char*)SB(b, h) + boff + (n * 2 + k) * 1024)
; #define WAIT_V(n) asm volatile("s_waitcnt vmcnt(" #n ")" ::: "memory")
; #define WAIT_L(n) asm volatile("s_waitcnt lgkmcnt(" #n ")" ::: "memory")
; #define BAR __builtin_amdgcn_s_barrier()
; #define SCHED __builtin_amdgcn_sched_barrier(0)
; __device__ __forceinline__ void gemm_phase(const int tid_, const GemmArgs& ga, u16* shm) {
;     ...
;       for (int t = 0; t < nt; t += 2) {
;         const bool last = t + 2 >= nt;
;         const unsigned pA1 = gA + (unsigned)(t + 1) * 128u;
;         const unsigned pA2 = last ? gAn : gA + (unsigned)(t + 2) * 128u;
;         const unsigned pB2 = last ? gBn : gB + (unsigned)(t + 2) * 128u;
;         LDB(B0, 0, 0); SCHED; LDA(At, 0, 0); STAGE_A(SAO(1, 1), pA1, HALF);
;         WAIT_L(8); BAR; WAIT_L(0); MMA(0, 0, At, B0); BAR; SCHED;
;         LDB(B1, 0, 1); STAGE_B(SBO(0, 0), pB2, 0);
;         BAR; WAIT_L(0); MMA(0, 1, At, B1); BAR;
;         LDA(At, 0, 1); STAGE_A(SAO(0, 0), pA2, 0);
;         BAR; WAIT_L(0); MMA(1, 0, At, B0); BAR; SCHED;
;         STAGE_B(SBO(0, 1), pB2, HALF);
;         WAIT_V(6); BAR; MMA(1, 1, At, B1); BAR;
.LBB0_316:
	v_add_u32_e32 v96, 0x10000, v224
	s_mov_b32 s6, s78
	ds_read_b128 v[132:135], v96
	ds_read_b128 v[136:139], v96 offset:1024
	ds_read_b128 v[140:143], v96 offset:2048
	ds_read_b128 v[144:147], v96 offset:3072
	s_add_i32 s78, s78, 2
	s_lshl_b32 s6, s6, 7
	s_lshl_b32 s7, s78, 7
	s_add_i32 s10, s79, s6
	s_add_i32 s8, s7, s54
	s_add_i32 s9, s7, s1
	s_add_i32 s11, s10, s62
	s_cmp_ge_u32 s78, s67
	s_cselect_b64 s[28:29], -1, 0
	s_and_b64 s[6:7], s[28:29], exec
	s_cselect_b32 s6, s19, s8
	ds_read_b128 v[152:155], v225
	ds_read_b128 v[156:159], v225 offset:1024
	ds_read_b128 v[160:163], v225 offset:2048
	ds_read_b128 v[164:167], v225 offset:3072
	ds_read_b128 v[168:171], v225 offset:4096
	ds_read_b128 v[172:175], v225 offset:5120
	ds_read_b128 v[176:179], v225 offset:6144
	s_mov_b32 m0, s66
	ds_read_b128 v[180:183], v225 offset:7168
	buffer_load_dwordx4 v222, s[48:51], s10 offen lds
	s_mov_b32 m0, s18
	s_nop 0
	buffer_load_dwordx4 v222, s[48:51], s11 offen lds
	v_add_u32_e32 v96, 0x14000, v224
	ds_read_b128 v[184:187], v96
	ds_read_b128 v[188:191], v96 offset:1024
	ds_read_b128 v[192:195], v96 offset:2048
	ds_read_b128 v[196:199], v96 offset:3072
	s_waitcnt lgkmcnt(0)
	s_waitcnt vmcnt(8)
	s_barrier
	v_mfma_f32_16x16x32_bf16 v[128:131], v[132:135], v[152:155], v[128:131]
	v_mfma_f32_16x16x32_bf16 v[124:127], v[140:143], v[152:155], v[124:127]
	v_mfma_f32_16x16x32_bf16 v[120:123], v[132:135], v[160:163], v[120:123]
	v_mfma_f32_16x16x32_bf16 v[116:119], v[140:143], v[160:163], v[116:119]
	v_mfma_f32_16x16x32_bf16 v[112:115], v[132:135], v[168:171], v[112:115]
	v_mfma_f32_16x16x32_bf16 v[108:111], v[140:143], v[168:171], v[108:111]
	v_mfma_f32_16x16x32_bf16 v[104:107], v[132:135], v[176:179], v[104:107]
	v_mfma_f32_16x16x32_bf16 v[98:101], v[140:143], v[176:179], v[100:103]
	v_mfma_f32_16x16x32_bf16 v[128:131], v[136:139], v[156:159], v[128:131]
	v_mfma_f32_16x16x32_bf16 v[124:127], v[144:147], v[156:159], v[124:127]
	v_mfma_f32_16x16x32_bf16 v[120:123], v[136:139], v[164:167], v[120:123]
	v_mfma_f32_16x16x32_bf16 v[116:119], v[144:147], v[164:167], v[116:119]
	v_mfma_f32_16x16x32_bf16 v[112:115], v[136:139], v[172:175], v[112:115]
	v_mfma_f32_16x16x32_bf16 v[108:111], v[144:147], v[172:175], v[108:111]
	v_mfma_f32_16x16x32_bf16 v[102:105], v[136:139], v[180:183], v[104:107]
	v_mfma_f32_16x16x32_bf16 v[98:101], v[144:147], v[180:183], v[98:101]
	v_mfma_f32_16x16x32_bf16 v[92:95], v[184:187], v[152:155], v[92:95]
	v_mfma_f32_16x16x32_bf16 v[88:91], v[192:195], v[152:155], v[88:91]
	v_mfma_f32_16x16x32_bf16 v[84:87], v[184:187], v[160:163], v[84:87]
	v_mfma_f32_16x16x32_bf16 v[80:83], v[192:195], v[160:163], v[80:83]
	v_mfma_f32_16x16x32_bf16 v[76:79], v[184:187], v[168:171], v[76:79]
	v_mfma_f32_16x16x32_bf16 v[72:75], v[192:195], v[168:171], v[72:75]
	v_mfma_f32_16x16x32_bf16 v[68:71], v[184:187], v[176:179], v[68:71]
	v_mfma_f32_16x16x32_bf16 v[64:67], v[192:195], v[176:179], v[64:67]
	v_mfma_f32_16x16x32_bf16 v[92:95], v[188:191], v[156:159], v[92:95]
	v_mfma_f32_16x16x32_bf16 v[88:91], v[196:199], v[156:159], v[88:91]
	v_mfma_f32_16x16x32_bf16 v[84:87], v[188:191], v[164:167], v[84:87]
	v_mfma_f32_16x16x32_bf16 v[80:83], v[196:199], v[164:167], v[80:83]
	v_mfma_f32_16x16x32_bf16 v[76:79], v[188:191], v[172:175], v[76:79]
	v_mfma_f32_16x16x32_bf16 v[72:75], v[196:199], v[172:175], v[72:75]
	v_mfma_f32_16x16x32_bf16 v[68:71], v[188:191], v[180:183], v[68:71]
	v_mfma_f32_16x16x32_bf16 v[64:67], v[196:199], v[180:183], v[64:67]
	s_barrier
	ds_read_b128 v[152:155], v225 offset:16384
	ds_read_b128 v[156:159], v225 offset:17408
	ds_read_b128 v[160:163], v225 offset:18432
	ds_read_b128 v[164:167], v225 offset:19456
	ds_read_b128 v[168:171], v225 offset:20480
	ds_read_b128 v[172:175], v225 offset:21504
	ds_read_b128 v[176:179], v225 offset:22528
	ds_read_b128 v[180:183], v225 offset:23552
	s_mov_b32 m0, s65
	s_cselect_b32 s7, s64, s9
	buffer_load_dwordx4 v223, s[44:47], s7 offen lds
	s_mov_b32 m0, s72
	s_add_i32 s8, s7, s63
	buffer_load_dwordx4 v223, s[44:47], s8 offen lds
	s_mov_b32 m0, s55
	s_nop 0
	buffer_load_dwordx4 v222, s[48:51], s6 offen lds
	s_mov_b32 m0, s73
	s_add_i32 s9, s6, s62
	buffer_load_dwordx4 v222, s[48:51], s9 offen lds
	s_mov_b32 m0, s52
	s_add_i32 s8, s8, s63
	buffer_load_dwordx4 v223, s[44:47], s8 offen lds
	s_mov_b32 m0, s58
	s_add_i32 s8, s8, s63
	buffer_load_dwordx4 v223, s[44:47], s8 offen lds
	s_waitcnt lgkmcnt(0)
	s_waitcnt vmcnt(8)
	s_barrier
	v_mfma_f32_16x16x32_bf16 v[60:63], v[132:135], v[152:155], v[60:63]
	v_mfma_f32_16x16x32_bf16 v[56:59], v[140:143], v[152:155], v[56:59]
	v_mfma_f32_16x16x32_bf16 v[52:55], v[132:135], v[160:163], v[52:55]
	v_mfma_f32_16x16x32_bf16 v[48:51], v[140:143], v[160:163], v[48:51]
	v_mfma_f32_16x16x32_bf16 v[44:47], v[132:135], v[168:171], v[44:47]
	v_mfma_f32_16x16x32_bf16 v[40:43], v[140:143], v[168:171], v[40:43]
	v_mfma_f32_16x16x32_bf16 v[36:39], v[132:135], v[176:179], v[36:39]
	v_mfma_f32_16x16x32_bf16 v[32:35], v[140:143], v[176:179], v[32:35]
	v_mfma_f32_16x16x32_bf16 v[60:63], v[136:139], v[156:159], v[60:63]
	v_mfma_f32_16x16x32_bf16 v[56:59], v[144:147], v[156:159], v[56:59]
	v_mfma_f32_16x16x32_bf16 v[52:55], v[136:139], v[164:167], v[52:55]
	v_mfma_f32_16x16x32_bf16 v[48:51], v[144:147], v[164:167], v[48:51]
	v_mfma_f32_16x16x32_bf16 v[44:47], v[136:139], v[172:175], v[44:47]
	v_mfma_f32_16x16x32_bf16 v[40:43], v[144:147], v[172:175], v[40:43]
	v_mfma_f32_16x16x32_bf16 v[36:39], v[136:139], v[180:183], v[36:39]
	v_mfma_f32_16x16x32_bf16 v[32:35], v[144:147], v[180:183], v[32:35]
	v_mfma_f32_16x16x32_bf16 v[28:31], v[184:187], v[152:155], v[28:31]
	v_mfma_f32_16x16x32_bf16 v[24:27], v[192:195], v[152:155], v[24:27]
	v_mfma_f32_16x16x32_bf16 v[20:23], v[184:187], v[160:163], v[20:23]
	v_mfma_f32_16x16x32_bf16 v[16:19], v[192:195], v[160:163], v[16:19]
	v_mfma_f32_16x16x32_bf16 v[12:15], v[184:187], v[168:171], v[12:15]
	v_mfma_f32_16x16x32_bf16 v[8:11], v[192:195], v[168:171], v[8:11]
	v_mfma_f32_16x16x32_bf16 v[4:7], v[184:187], v[176:179], v[4:7]
	v_mfma_f32_16x16x32_bf16 v[0:3], v[192:195], v[176:179], v[0:3]
	v_mfma_f32_16x16x32_bf16 v[28:31], v[188:191], v[156:159], v[28:31]
	v_mfma_f32_16x16x32_bf16 v[24:27], v[196:199], v[156:159], v[24:27]
	v_mfma_f32_16x16x32_bf16 v[20:23], v[188:191], v[164:167], v[20:23]
	v_mfma_f32_16x16x32_bf16 v[16:19], v[196:199], v[164:167], v[16:19]
	v_mfma_f32_16x16x32_bf16 v[12:15], v[188:191], v[172:175], v[12:15]
	v_mfma_f32_16x16x32_bf16 v[8:11], v[196:199], v[172:175], v[8:11]
	v_mfma_f32_16x16x32_bf16 v[4:7], v[188:191], v[180:183], v[4:7]
	v_mfma_f32_16x16x32_bf16 v[0:3], v[196:199], v[180:183], v[0:3]
	s_barrier
; #define STAGE_A(Poff, off, hrow) do { const unsigned _s = (off) + (unsigned)(hrow) * lda2;                                \
;     GLDS(ldsw + (Poff), offA, srdA, _s); GLDS(ldsw + (Poff) + 8192, offA, srdA, _s + lda128); } while (0)
; #define STAGE_B(Poff, off, hrow) do { const unsigned _s = (off) + (unsigned)(hrow) * ldb2;                                \
;     GLDS(ldsw + (Poff), offB, srdB, _s); GLDS(ldsw + (Poff) + 8192, offB, srdB, _s + ldb128); } while (0)
; #define LDA(dst, b, h) _Pragma("unroll") for (int m = 0; m < 4; ++m) _Pragma("unroll") for (int k = 0; k < 2; ++k) \
;     dst[m][k] = *reinterpret_cast<const bf16x8*>((const char*)SA(b, h) + aoff + (m * 2 + k) * 1024)
; #define LDB(dst, b, h) _Pragma("unroll") for (int n = 0; n < 2; ++n) _Pragma("unroll") for (int k = 0; k < 2; ++k) \
;     dst[n][k] = *reinterpret_cast<const bf16x8*>((const char*)SB(b, h) + boff + (n * 2 + k) * 1024)
; #define WAIT_V(n) asm volatile("s_waitcnt vmcnt(" #n ")" ::: "memory")
; #define WAIT_L(n) asm volatile("s_waitcnt lgkmcnt(" #n ")" ::: "memory")
; #define BAR __builtin_amdgcn_s_barrier()
; #define SCHED __builtin_amdgcn_sched_barrier(0)
; __device__ __forceinline__ void gemm_phase(const int tid_, const GemmArgs& ga, u16* shm) {
;     ...
;         LDB(B0, 1, 0); SCHED; LDA(At, 1, 0); STAGE_A(SAO(0, 1), pA2, HALF);
;         WAIT_L(8); BAR; WAIT_L(0); MMA(0, 0, At, B0); BAR; SCHED;
;         LDB(B1, 1, 1); STAGE_B(SBO(1, 0), pB2 + 128, 0);
;         BAR; WAIT_L(0); MMA(0, 1, At, B1); BAR;
;         LDA(At, 1, 1); STAGE_A(SAO(1, 0), pA2 + 128, 0);
;         BAR; WAIT_L(0); MMA(1, 0, At, B0); BAR; SCHED;
;         STAGE_B(SBO(1, 1), pB2 + 128, HALF);
;         WAIT_V(6); BAR; MMA(1, 1, At, B1);
; #pragma nounroll
;         for (int pass = 0; pass < 2; ++pass) {
;           if (last && wr == 1 - pass) {
;       gemm_epilogue(tid_, ga, brow, bcol, acc, (char*)shm + 131072);
; #pragma unroll
;             for (int ai = 0; ai < 2; ++ai)
; #pragma unroll
;               for (int bj = 0; bj < 2; ++bj)
; #pragma unroll
;                 for (int m = 0; m < 4; ++m)
; #pragma unroll
;                   for (int n = 0; n < 2; ++n) acc[ai][bj][m][n] = f32x4{0.f, 0.f, 0.f, 0.f};
;           }
;           if (pass == 0) BAR;
;         }
;       }
;       if (!has_next) break;
	v_add_u32_e32 v96, 0x18000, v224
	ds_read_b128 v[132:135], v96
	ds_read_b128 v[136:139], v96 offset:1024
	ds_read_b128 v[140:143], v96 offset:2048
	ds_read_b128 v[144:147], v96 offset:3072
	ds_read_b128 v[152:155], v225 offset:32768
	ds_read_b128 v[156:159], v225 offset:33792
	ds_read_b128 v[160:163], v225 offset:34816
	ds_read_b128 v[164:167], v225 offset:35840
	ds_read_b128 v[168:171], v225 offset:36864
	ds_read_b128 v[172:175], v225 offset:37888
	ds_read_b128 v[176:179], v225 offset:38912
	ds_read_b128 v[180:183], v225 offset:39936
	v_add_u32_e32 v96, 0x1c000, v224
	ds_read_b128 v[184:187], v96
	ds_read_b128 v[188:191], v96 offset:1024
	ds_read_b128 v[192:195], v96 offset:2048
	ds_read_b128 v[196:199], v96 offset:3072
	s_mov_b32 m0, s59
	s_add_i32 s8, s9, s62
	buffer_load_dwordx4 v222, s[48:51], s8 offen lds
	s_mov_b32 m0, s2
	s_add_i32 s8, s8, s62
	buffer_load_dwordx4 v222, s[48:51], s8 offen lds
	s_waitcnt lgkmcnt(0)
	s_waitcnt vmcnt(8)
	s_barrier
	v_mfma_f32_16x16x32_bf16 v[128:131], v[132:135], v[152:155], v[128:131]
	v_mfma_f32_16x16x32_bf16 v[124:127], v[140:143], v[152:155], v[124:127]
	v_mfma_f32_16x16x32_bf16 v[120:123], v[132:135], v[160:163], v[120:123]
	v_mfma_f32_16x16x32_bf16 v[116:119], v[140:143], v[160:163], v[116:119]
	v_mfma_f32_16x16x32_bf16 v[112:115], v[132:135], v[168:171], v[112:115]
	v_mfma_f32_16x16x32_bf16 v[106:109], v[140:143], v[168:171], v[108:111]
	v_mfma_f32_16x16x32_bf16 v[102:105], v[132:135], v[176:179], v[102:105]
	v_mfma_f32_16x16x32_bf16 v[98:101], v[140:143], v[176:179], v[98:101]
	v_mfma_f32_16x16x32_bf16 v[128:131], v[136:139], v[156:159], v[128:131]
	v_mfma_f32_16x16x32_bf16 v[124:127], v[144:147], v[156:159], v[124:127]
	v_mfma_f32_16x16x32_bf16 v[120:123], v[136:139], v[164:167], v[120:123]
	v_mfma_f32_16x16x32_bf16 v[116:119], v[144:147], v[164:167], v[116:119]
	v_mfma_f32_16x16x32_bf16 v[112:115], v[136:139], v[172:175], v[112:115]
	v_mfma_f32_16x16x32_bf16 v[108:111], v[144:147], v[172:175], v[106:109]
	v_mfma_f32_16x16x32_bf16 v[104:107], v[136:139], v[180:183], v[102:105]
	v_mfma_f32_16x16x32_bf16 v[100:103], v[144:147], v[180:183], v[98:101]
	v_mfma_f32_16x16x32_bf16 v[92:95], v[184:187], v[152:155], v[92:95]
	v_mfma_f32_16x16x32_bf16 v[88:91], v[192:195], v[152:155], v[88:91]
	v_mfma_f32_16x16x32_bf16 v[84:87], v[184:187], v[160:163], v[84:87]
	v_mfma_f32_16x16x32_bf16 v[80:83], v[192:195], v[160:163], v[80:83]
	v_mfma_f32_16x16x32_bf16 v[76:79], v[184:187], v[168:171], v[76:79]
	v_mfma_f32_16x16x32_bf16 v[72:75], v[192:195], v[168:171], v[72:75]
	v_mfma_f32_16x16x32_bf16 v[68:71], v[184:187], v[176:179], v[68:71]
	v_mfma_f32_16x16x32_bf16 v[64:67], v[192:195], v[176:179], v[64:67]
	v_mfma_f32_16x16x32_bf16 v[92:95], v[188:191], v[156:159], v[92:95]
	v_mfma_f32_16x16x32_bf16 v[88:91], v[196:199], v[156:159], v[88:91]
	v_mfma_f32_16x16x32_bf16 v[84:87], v[188:191], v[164:167], v[84:87]
	v_mfma_f32_16x16x32_bf16 v[80:83], v[196:199], v[164:167], v[80:83]
	v_mfma_f32_16x16x32_bf16 v[76:79], v[188:191], v[172:175], v[76:79]
	v_mfma_f32_16x16x32_bf16 v[72:75], v[196:199], v[172:175], v[72:75]
	v_mfma_f32_16x16x32_bf16 v[68:71], v[188:191], v[180:183], v[68:71]
	v_mfma_f32_16x16x32_bf16 v[64:67], v[196:199], v[180:183], v[64:67]
	s_barrier
	ds_read_b128 v[152:155], v225 offset:49152
	ds_read_b128 v[156:159], v225 offset:50176
	ds_read_b128 v[160:163], v225 offset:51200
	ds_read_b128 v[164:167], v225 offset:52224
	ds_read_b128 v[168:171], v225 offset:53248
	ds_read_b128 v[172:175], v225 offset:54272
	ds_read_b128 v[176:179], v225 offset:55296
	ds_read_b128 v[180:183], v225 offset:56320
	s_mov_b32 m0, s98
	s_addk_i32 s7, 0x80
	buffer_load_dwordx4 v223, s[44:47], s7 offen lds
	s_mov_b32 m0, s99
	s_add_i32 s7, s7, s63
	buffer_load_dwordx4 v223, s[44:47], s7 offen lds
	s_mov_b32 m0, s68
	s_addk_i32 s6, 0x80
	buffer_load_dwordx4 v222, s[48:51], s6 offen lds
	s_mov_b32 m0, s69
	s_add_i32 s6, s6, s62
	buffer_load_dwordx4 v222, s[48:51], s6 offen lds
	s_mov_b32 m0, s42
	s_add_i32 s6, s7, s63
	buffer_load_dwordx4 v223, s[44:47], s6 offen lds
	s_mov_b32 m0, s43
	s_add_i32 s6, s6, s63
	buffer_load_dwordx4 v223, s[44:47], s6 offen lds
	s_waitcnt lgkmcnt(0)
	s_waitcnt vmcnt(8)
	s_barrier
	v_mfma_f32_16x16x32_bf16 v[60:63], v[132:135], v[152:155], v[60:63]
	v_mfma_f32_16x16x32_bf16 v[56:59], v[140:143], v[152:155], v[56:59]
	v_mfma_f32_16x16x32_bf16 v[52:55], v[132:135], v[160:163], v[52:55]
	v_mfma_f32_16x16x32_bf16 v[48:51], v[140:143], v[160:163], v[48:51]
	v_mfma_f32_16x16x32_bf16 v[44:47], v[132:135], v[168:171], v[44:47]
	v_mfma_f32_16x16x32_bf16 v[40:43], v[140:143], v[168:171], v[40:43]
	v_mfma_f32_16x16x32_bf16 v[36:39], v[132:135], v[176:179], v[36:39]
	v_mfma_f32_16x16x32_bf16 v[32:35], v[140:143], v[176:179], v[32:35]
	v_mfma_f32_16x16x32_bf16 v[60:63], v[136:139], v[156:159], v[60:63]
	v_mfma_f32_16x16x32_bf16 v[56:59], v[144:147], v[156:159], v[56:59]
	v_mfma_f32_16x16x32_bf16 v[52:55], v[136:139], v[164:167], v[52:55]
	v_mfma_f32_16x16x32_bf16 v[48:51], v[144:147], v[164:167], v[48:51]
	v_mfma_f32_16x16x32_bf16 v[44:47], v[136:139], v[172:175], v[44:47]
	v_mfma_f32_16x16x32_bf16 v[40:43], v[144:147], v[172:175], v[40:43]
	v_mfma_f32_16x16x32_bf16 v[36:39], v[136:139], v[180:183], v[36:39]
	v_mfma_f32_16x16x32_bf16 v[32:35], v[144:147], v[180:183], v[32:35]
	v_mfma_f32_16x16x32_bf16 v[28:31], v[184:187], v[152:155], v[28:31]
	v_mfma_f32_16x16x32_bf16 v[24:27], v[192:195], v[152:155], v[24:27]
	v_mfma_f32_16x16x32_bf16 v[20:23], v[184:187], v[160:163], v[20:23]
	v_mfma_f32_16x16x32_bf16 v[16:19], v[192:195], v[160:163], v[16:19]
	v_mfma_f32_16x16x32_bf16 v[12:15], v[184:187], v[168:171], v[12:15]
	v_mfma_f32_16x16x32_bf16 v[8:11], v[192:195], v[168:171], v[8:11]
	v_mfma_f32_16x16x32_bf16 v[4:7], v[184:187], v[176:179], v[4:7]
	v_mfma_f32_16x16x32_bf16 v[0:3], v[192:195], v[176:179], v[0:3]
	v_mfma_f32_16x16x32_bf16 v[28:31], v[188:191], v[156:159], v[28:31]
	v_mfma_f32_16x16x32_bf16 v[24:27], v[196:199], v[156:159], v[24:27]
	v_mfma_f32_16x16x32_bf16 v[20:23], v[188:191], v[164:167], v[20:23]
	v_mfma_f32_16x16x32_bf16 v[16:19], v[196:199], v[164:167], v[16:19]
	v_mfma_f32_16x16x32_bf16 v[12:15], v[188:191], v[172:175], v[12:15]
	v_mfma_f32_16x16x32_bf16 v[8:11], v[196:199], v[172:175], v[8:11]
	v_mfma_f32_16x16x32_bf16 v[4:7], v[188:191], v[180:183], v[4:7]
	v_mfma_f32_16x16x32_bf16 v[0:3], v[196:199], v[180:183], v[0:3]
	s_cmp_eq_u64 s[28:29], 0
	s_cbranch_scc0 .Lg_seam
	s_barrier
	s_branch .LBB0_316
.Lg_seam:
	s_mov_b64 s[30:31], -1
	s_mov_b32 s8, 0
	s_branch .LBB0_318
